# v034 + HGRN: s_setprio 1 for the critical wave half in each stage (waves 0-3 in stage 1, waves 4-7 in stage 2), reset at chunk-loop top
# baseline (speedup 1.0000x reference)
; template <int LO, int HI>
; __global__ void __launch_bounds__(512, 2) mega(Params p) {
;     ...
;     if constexpr (IN(4)) {
;         for (int item = vcu; item < 256; item += G) hgrn_phase(lds, BIG, Y, item);
;     }
.LBB0_498:
	s_setprio 0
	s_add_i32 s73, s73, s72
	s_mov_b64 s[90:91], s[80:81]
	v_readlane_b32 s80, v255, 2
	s_mov_b32 s86, s72
	s_cmpk_gt_i32 s73, 0xff
	s_mov_b64 s[88:89], s[76:77]
	v_readlane_b32 s81, v255, 3
	s_mov_b64 s[92:93], s[70:71]
	s_waitcnt lgkmcnt(0)
	s_barrier
	s_cbranch_scc1 .LBB0_522

; #define LAS __attribute__((address_space(3)))
; __device__ __forceinline__ float bflo(unsigned u) { return __uint_as_float(u << 16); }
; __device__ __forceinline__ float bfhi(unsigned u) { return __uint_as_float(u & 0xffff0000u); }
; #define HG_BAR() asm volatile("s_waitcnt lgkmcnt(0)\n\ts_barrier" ::: "memory")
; #define HG_LOAD(c_, q_, k_, v_) do { _Pragma("unroll") for (int j = 0; j < 8; ++j) { const size_t off = (tok0 + HG_TOK(c_, 8 * wid + j)) * 512 + hh * 128 + 2 * lane; \
;         q_[j] = *(const unsigned*)(QR + off); k_[j] = *(const unsigned*)(KK + off); } \
;         v_ = *(const u32x4*)(IR + (tok0 + HG_TOK(c_, tv)) * 512 + hh * 128 + dvh * 64 + cv * 8); } while (0)
; __device__ __forceinline__ void hgrn_phase(LAS unsigned char* lds, const bf16_t* mix, bf16_t* OFB, int item) {
;     ...
;     HG_LOAD(0, cq, ck, cvv);
;     __syncthreads();
;     for (int c = 0; c < 64; ++c) {
;         float c0[8], c1[8];
;         { float a0 = 1.f, a1 = 1.f;
; #pragma unroll
;           for (int j = 0; j < 8; ++j) { a0 *= 1.0f - bflo(ck[j]); a1 *= 1.0f - bfhi(ck[j]); c0[j] = a0; c1[j] = a1; } }
;         *(LAS f32x2*)(lds + HG_SEG + (wid * 128 + 2 * lane) * 4) = (f32x2){c0[7], c1[7]};
;         unsigned nq[8], nk[8]; u32x4 nv;
;         { const int cn = (c + 1 < 64) ? c + 1 : 63; HG_LOAD(cn, nq, nk, nv); }
;         HG_BAR();
;         float pre0 = 1.f, pre1 = 1.f, mid0 = 1.f, mid1 = 1.f, last0 = 1.f, last1 = 1.f;
; #pragma unroll
;         for (int s = 0; s < 8; ++s) { const f32x2 tt = *(LAS const f32x2*)(lds + HG_SEG + (s * 128 + 2 * lane) * 4);
;             pre0 *= (s < wid) ? tt[0] : 1.f; pre1 *= (s < wid) ? tt[1] : 1.f; if (s < 4) { mid0 *= tt[0]; mid1 *= tt[1]; } last0 *= tt[0]; last1 *= tt[1]; }
.LBB0_507:
	s_setprio 0
	s_add_i32 s74, s78, 1
	s_cmp_lg_u32 s78, 63
	s_cselect_b32 s92, s74, 63
	s_lshl_b32 s75, s92, 6
	s_add_i32 s93, s75, s33
	s_sub_i32 vcc_lo, 0xfff, s93
	s_and_b64 s[56:57], s[4:5], exec
	s_cselect_b32 s56, s93, vcc_lo
	s_ashr_i32 s57, s56, 31
	s_add_u32 s56, s90, s56
	s_addc_u32 s57, s91, s57
	s_lshl_b64 s[56:57], s[56:57], 10
	v_or_b32_e32 v38, s56, v80
	s_add_i32 s56, s68, s75
	s_sub_i32 vcc_lo, 0xfff, s56
	s_or_b32 vcc_hi, s93, 1
	v_mov_b32_e32 v39, s57
	s_and_b64 s[56:57], s[4:5], exec
	s_cselect_b32 s56, vcc_hi, vcc_lo
	s_ashr_i32 s57, s56, 31
	s_add_u32 s56, s90, s56
	s_addc_u32 s57, s91, s57
	s_lshl_b64 s[56:57], s[56:57], 10
	v_or_b32_e32 v42, s56, v80
	s_add_i32 s56, s95, s75
	s_sub_i32 vcc_lo, 0xfff, s56
	s_or_b32 vcc_hi, s93, 2
	v_mov_b32_e32 v43, s57
	s_and_b64 s[56:57], s[4:5], exec
	s_cselect_b32 s56, vcc_hi, vcc_lo
	s_ashr_i32 s57, s56, 31
	s_add_u32 s56, s90, s56
	s_addc_u32 s57, s91, s57
	s_lshl_b64 s[56:57], s[56:57], 10
	v_or_b32_e32 v46, s56, v80
	s_add_i32 s56, s94, s75
	s_sub_i32 vcc_lo, 0xfff, s56
	s_or_b32 vcc_hi, s93, 3
	v_mov_b32_e32 v47, s57
	s_and_b64 s[56:57], s[4:5], exec
	s_cselect_b32 s56, vcc_hi, vcc_lo
	s_ashr_i32 s57, s56, 31
	s_add_u32 s56, s90, s56
	s_addc_u32 s57, s91, s57
	s_lshl_b64 s[56:57], s[56:57], 10
	v_or_b32_e32 v50, s56, v80
	s_add_i32 s56, s97, s75
	s_sub_i32 vcc_lo, 0xfff, s56
	s_or_b32 vcc_hi, s93, 4
	v_mov_b32_e32 v51, s57
	s_and_b64 s[56:57], s[4:5], exec
	s_cselect_b32 s56, vcc_hi, vcc_lo
	s_ashr_i32 s57, s56, 31
	s_add_u32 s56, s90, s56
	s_addc_u32 s57, s91, s57
	v_lshl_add_u64 v[40:41], s[82:83], 0, v[38:39]
	v_lshl_add_u64 v[38:39], s[88:89], 0, v[38:39]
	s_lshl_b64 s[56:57], s[56:57], 10
	s_waitcnt vmcnt(15)
	v_lshlrev_b32_e32 v36, 16, v75
	v_and_b32_e32 v37, 0xffff0000, v75
	s_waitcnt vmcnt(13)
	v_lshlrev_b32_e32 v34, 16, v76
	v_and_b32_e32 v35, 0xffff0000, v76
	s_waitcnt vmcnt(11)
	v_lshlrev_b32_e32 v32, 16, v77
	v_and_b32_e32 v33, 0xffff0000, v77
	s_waitcnt vmcnt(9)
	v_lshlrev_b32_e32 v14, 16, v78
	v_and_b32_e32 v15, 0xffff0000, v78
	v_lshl_add_u64 v[44:45], s[82:83], 0, v[42:43]
	v_lshl_add_u64 v[42:43], s[88:89], 0, v[42:43]
	v_lshl_add_u64 v[48:49], s[82:83], 0, v[46:47]
	v_lshl_add_u64 v[46:47], s[88:89], 0, v[46:47]
	v_lshl_add_u64 v[58:59], s[82:83], 0, v[50:51]
	v_lshl_add_u64 v[50:51], s[88:89], 0, v[50:51]
	global_load_dword v92, v[40:41], off
	global_load_dword v75, v[38:39], off
	global_load_dword v93, v[44:45], off
	global_load_dword v76, v[42:43], off
	global_load_dword v94, v[48:49], off
	global_load_dword v77, v[46:47], off
	global_load_dword v95, v[58:59], off
	global_load_dword v78, v[50:51], off
	v_or_b32_e32 v38, s56, v80
	s_add_i32 s56, s96, s75
	s_sub_i32 vcc_lo, 0xfff, s56
	s_or_b32 vcc_hi, s93, 5
	v_mov_b32_e32 v39, s57
	s_and_b64 s[56:57], s[4:5], exec
	s_cselect_b32 s56, vcc_hi, vcc_lo
	s_ashr_i32 s57, s56, 31
	s_add_u32 s56, s90, s56
	s_addc_u32 s57, s91, s57
	s_lshl_b64 s[56:57], s[56:57], 10
	v_or_b32_e32 v42, s56, v80
	s_add_i32 s56, s60, s75
	s_sub_i32 vcc_lo, 0xfff, s56
	s_or_b32 vcc_hi, s93, 6
	v_mov_b32_e32 v43, s57
	s_and_b64 s[56:57], s[4:5], exec
	s_cselect_b32 s56, vcc_hi, vcc_lo
	s_ashr_i32 s57, s56, 31
	s_add_u32 s56, s90, s56
	s_addc_u32 s57, s91, s57
	s_lshl_b64 s[56:57], s[56:57], 10
	v_or_b32_e32 v46, s56, v80
	s_add_i32 s56, s61, s75
	s_sub_i32 vcc_lo, 0xfff, s56
	s_or_b32 s93, s93, 7
	v_mov_b32_e32 v47, s57
	s_and_b64 s[56:57], s[4:5], exec
	s_cselect_b32 s56, s93, vcc_lo
	s_ashr_i32 s57, s56, 31
	s_add_u32 s56, s90, s56
	s_addc_u32 s57, s91, s57
	s_lshl_b64 s[56:57], s[56:57], 10
	v_lshl_add_u64 v[40:41], s[82:83], 0, v[38:39]
	v_or_b32_e32 v50, s56, v80
	v_mov_b32_e32 v51, s57
	s_waitcnt vmcnt(15)
	v_lshlrev_b32_e32 v12, 16, v89
	v_and_b32_e32 v13, 0xffff0000, v89
	s_waitcnt vmcnt(13)
	v_lshlrev_b32_e32 v10, 16, v90
	v_and_b32_e32 v11, 0xffff0000, v90
	s_waitcnt vmcnt(11)
	v_lshlrev_b32_e32 v8, 16, v91
	v_and_b32_e32 v9, 0xffff0000, v91
	s_waitcnt vmcnt(9)
	v_lshlrev_b32_e32 v6, 16, v88
	v_and_b32_e32 v7, 0xffff0000, v88
	v_lshl_add_u64 v[38:39], s[88:89], 0, v[38:39]
	v_lshl_add_u64 v[44:45], s[82:83], 0, v[42:43]
	v_lshl_add_u64 v[42:43], s[88:89], 0, v[42:43]
	v_lshl_add_u64 v[48:49], s[82:83], 0, v[46:47]
	v_lshl_add_u64 v[46:47], s[88:89], 0, v[46:47]
	v_lshl_add_u64 v[58:59], s[82:83], 0, v[50:51]
	v_lshl_add_u64 v[50:51], s[88:89], 0, v[50:51]
	global_load_dword v96, v[40:41], off
	global_load_dword v89, v[38:39], off
	global_load_dword v97, v[44:45], off
	global_load_dword v90, v[42:43], off
	global_load_dword v98, v[48:49], off
	global_load_dword v91, v[46:47], off
	global_load_dword v99, v[58:59], off
	global_load_dword v88, v[50:51], off
	v_pk_add_f32 v[64:65], v[36:37], 1.0 op_sel_hi:[1,0] neg_lo:[1,0] neg_hi:[1,0]
	v_pk_add_f32 v[38:39], v[34:35], 1.0 op_sel_hi:[1,0] neg_lo:[1,0] neg_hi:[1,0]
	v_add_u32_e32 v44, s79, v69
	v_pk_mul_f32 v[62:63], v[64:65], v[38:39]
	v_pk_add_f32 v[38:39], v[32:33], 1.0 op_sel_hi:[1,0] neg_lo:[1,0] neg_hi:[1,0]
	s_andn2_b64 vcc, exec, s[64:65]
	v_pk_mul_f32 v[60:61], v[62:63], v[38:39]
	v_pk_add_f32 v[38:39], v[14:15], 1.0 op_sel_hi:[1,0] neg_lo:[1,0] neg_hi:[1,0]
	s_mov_b64 s[56:57], -1
	v_pk_mul_f32 v[58:59], v[60:61], v[38:39]
	v_pk_add_f32 v[38:39], v[12:13], 1.0 op_sel_hi:[1,0] neg_lo:[1,0] neg_hi:[1,0]
	s_nop 0
	v_pk_mul_f32 v[46:47], v[58:59], v[38:39]
	v_pk_add_f32 v[38:39], v[10:11], 1.0 op_sel_hi:[1,0] neg_lo:[1,0] neg_hi:[1,0]
	s_nop 0
	v_pk_mul_f32 v[42:43], v[46:47], v[38:39]
	v_pk_add_f32 v[38:39], v[8:9], 1.0 op_sel_hi:[1,0] neg_lo:[1,0] neg_hi:[1,0]
	s_nop 0
	v_pk_mul_f32 v[40:41], v[42:43], v[38:39]
	v_pk_add_f32 v[38:39], v[6:7], 1.0 op_sel_hi:[1,0] neg_lo:[1,0] neg_hi:[1,0]
	s_nop 0
	v_pk_mul_f32 v[38:39], v[40:41], v[38:39]
	ds_write_b64 v44, v[38:39]
	s_cbranch_vccnz .LBB0_509
	v_lshl_add_u32 v44, s92, 6, v68
	v_sub_u32_e32 v44, 0xfff, v44
	s_mov_b64 s[56:57], 0

; #define LAS __attribute__((address_space(3)))
; __device__ __forceinline__ unsigned pkbf(float lo, float hi) { typedef __bf16 b2 __attribute__((ext_vector_type(2))); f32x2 v = {lo, hi}; b2 b = __builtin_convertvector(v, b2); return __builtin_bit_cast(unsigned, b); }
; __device__ __forceinline__ int crow(int i, int h) { return (i & 3) + 8 * (i >> 2) + 4 * h; }
; #define MFMA32(a, b, c) __builtin_amdgcn_mfma_f32_32x32x16_bf16((a), (b), (c), 0, 0, 0)
; __device__ __forceinline__ void hgrn_phase(LAS unsigned char* lds, const bf16_t* mix, bf16_t* OFB, int item) {
;     ...
;         if (wid < 4) {
;             if (xb <= tb) {
;                 f32x16 a;
; #pragma unroll
;                 for (int i = 0; i < 16; ++i) a[i] = 0.f;
; #pragma unroll
;                 for (int kh = 0; kh < 2; ++kh) { bf16x8 A[4], B[4];
; #pragma unroll
;                     for (int ks = 0; ks < 4; ++ks) { A[ks] = *(LAS const bf16x8*)(lds + HG_QI + (32 * tb + r) * HG_P + (16 * (4 * kh + ks) + 8 * h) * 2);
;                         B[ks] = *(LAS const bf16x8*)(lds + HG_KI + (32 * xb + r) * HG_P + (16 * (4 * kh + ks) + 8 * h) * 2); }
; #pragma unroll
;                     for (int ks = 0; ks < 4; ++ks) a = MFMA32(A[ks], B[ks], a);
;                 }
; #pragma unroll
;                 for (int i = 0; i < 16; ++i) { const int t = 32 * tb + crow(i, h), s = 32 * xb + r; const float v = (s <= t) ? a[i] : 0.f;
;                     *(LAS bf16_t*)(lds + HG_AS + t * HG_ASP + s * 2) = (bf16_t)(pkbf(v, v) & 0xffffu); }
.LBB0_515:
	s_andn2_b64 vcc, exec, s[92:93]
	s_cbranch_vccnz .LBB0_519
	s_andn2_b64 vcc, exec, s[0:1]
	s_cbranch_vccnz .LBB0_518
	s_setprio 1
	v_add_u32_e32 v1, v72, v54
	ds_read_b128 v[2:5], v1
	ds_read_b128 v[6:9], v82 offset:17408
	ds_read_b128 v[204:207], v1 offset:32
	ds_read_b128 v[208:211], v82 offset:17440
	ds_read_b128 v[212:215], v1 offset:64
	ds_read_b128 v[216:219], v82 offset:17472
	ds_read_b128 v[220:223], v1 offset:96
	ds_read_b128 v[224:227], v82 offset:17504
	s_waitcnt lgkmcnt(6)
	v_mfma_f32_32x32x16_bf16 v[32:47], v[2:5], v[6:9], 0
	ds_read_b128 v[2:5], v1 offset:128
	ds_read_b128 v[6:9], v82 offset:17536
	s_waitcnt lgkmcnt(6)
	v_mfma_f32_32x32x16_bf16 v[32:47], v[204:207], v[208:211], v[32:47]
	ds_read_b128 v[204:207], v1 offset:160
	ds_read_b128 v[208:211], v82 offset:17568
	s_waitcnt lgkmcnt(6)
	v_mfma_f32_32x32x16_bf16 v[32:47], v[212:215], v[216:219], v[32:47]
	ds_read_b128 v[212:215], v1 offset:192
	ds_read_b128 v[216:219], v82 offset:17600
	s_waitcnt lgkmcnt(6)
	v_mfma_f32_32x32x16_bf16 v[32:47], v[220:223], v[224:227], v[32:47]
	ds_read_b128 v[220:223], v1 offset:224
	ds_read_b128 v[224:227], v82 offset:17632
	s_waitcnt lgkmcnt(6)
	v_mfma_f32_32x32x16_bf16 v[32:47], v[2:5], v[6:9], v[32:47]
	s_waitcnt lgkmcnt(4)
	v_mfma_f32_32x32x16_bf16 v[32:47], v[204:207], v[208:211], v[32:47]
	s_waitcnt lgkmcnt(2)
	v_mfma_f32_32x32x16_bf16 v[32:47], v[212:215], v[216:219], v[32:47]
	s_waitcnt lgkmcnt(0)
	v_mfma_f32_32x32x16_bf16 v[32:47], v[220:223], v[224:227], v[32:47]
	s_nop 11
	v_cvt_pk_bf16_f32 v1, v32, s0
	v_cvt_pk_bf16_f32 v2, v33, s0
	v_cvt_pk_bf16_f32 v3, v34, s0
	v_cvt_pk_bf16_f32 v4, v35, s0
	v_cvt_pk_bf16_f32 v5, v36, s0
	v_cvt_pk_bf16_f32 v6, v37, s0
	v_cvt_pk_bf16_f32 v7, v38, s0
	v_cvt_pk_bf16_f32 v8, v39, s0
	v_cvt_pk_bf16_f32 v9, v40, s0
	v_cvt_pk_bf16_f32 v10, v41, s0
	v_cvt_pk_bf16_f32 v11, v42, s0
	v_cvt_pk_bf16_f32 v12, v43, s0
	v_cvt_pk_bf16_f32 v13, v44, s0
	v_cvt_pk_bf16_f32 v14, v45, s0
	v_cvt_pk_bf16_f32 v15, v46, s0
	v_cvt_pk_bf16_f32 v32, v47, s0
	v_cndmask_b32_e64 v1, v1, 0, s[22:23]
	v_cndmask_b32_e64 v2, v2, 0, s[24:25]
	v_cndmask_b32_e64 v3, v3, 0, s[26:27]
	v_cndmask_b32_e64 v4, v4, 0, s[28:29]
	v_cndmask_b32_e64 v5, v5, 0, s[30:31]
	v_cndmask_b32_e64 v6, v6, 0, s[34:35]
	v_cndmask_b32_e64 v7, v7, 0, s[36:37]
	v_cndmask_b32_e64 v8, v8, 0, s[38:39]
	v_cndmask_b32_e64 v9, v9, 0, s[40:41]
	v_cndmask_b32_e64 v10, v10, 0, s[42:43]
	v_cndmask_b32_e64 v11, v11, 0, s[44:45]
	v_cndmask_b32_e64 v12, v12, 0, s[46:47]
	v_cndmask_b32_e64 v13, v13, 0, s[48:49]
	v_cndmask_b32_e64 v14, v14, 0, s[50:51]
	v_cndmask_b32_e64 v15, v15, 0, s[52:53]
	v_cndmask_b32_e64 v32, v32, 0, s[54:55]
	ds_write_b16 v83, v1
	ds_write_b16 v83, v2 offset:144
	ds_write_b16 v83, v3 offset:288
	ds_write_b16 v83, v4 offset:432
	ds_write_b16 v83, v5 offset:1152
	ds_write_b16 v83, v6 offset:1296
	ds_write_b16 v83, v7 offset:1440
	ds_write_b16 v83, v8 offset:1584
	ds_write_b16 v83, v9 offset:2304
	ds_write_b16 v83, v10 offset:2448
	ds_write_b16 v83, v11 offset:2592
	ds_write_b16 v83, v12 offset:2736
	ds_write_b16 v83, v13 offset:3456
	ds_write_b16 v83, v14 offset:3600
	ds_write_b16 v83, v15 offset:3744
	ds_write_b16 v83, v32 offset:3888

; #define LAS __attribute__((address_space(3)))
; #define MFMA32(a, b, c) __builtin_amdgcn_mfma_f32_32x32x16_bf16((a), (b), (c), 0, 0, 0)
; __device__ __forceinline__ s16x4 trrd(LAS const unsigned char* p) { return __builtin_bit_cast(s16x4, __builtin_amdgcn_ds_read_tr16_b64_v4i16((LAS v4i16_t*)p)); }
; __device__ __forceinline__ bf16x8 cat8(s16x4 lo, s16x4 hi) { return (bf16x8){lo[0], lo[1], lo[2], lo[3], hi[0], hi[1], hi[2], hi[3]}; }
; #define HG_BAR() asm volatile("s_waitcnt lgkmcnt(0)\n\ts_barrier" ::: "memory")
; __device__ __forceinline__ void hgrn_phase(LAS unsigned char* lds, const bf16_t* mix, bf16_t* OFB, int item) {
;     ...
;         HG_BAR();
;         if (wid >= 4) {
;             const int nks = 2 * (tb + 1);
;             for (int ks = 0; ks < nks; ++ks) {
;                 const bf16x8 A = *(LAS const bf16x8*)(lds + HG_AS + (32 * tb + r) * HG_ASP + (16 * ks + 8 * h) * 2);
;                 LAS const unsigned char* vp = lds + HG_V + (16 * ks + trr) * HG_VP + (32 * xb + trc) * 2;
;                 const s16x4 lo = trrd(vp), hi = trrd(vp + 4 * HG_VP);
;                 oacc = MFMA32(cat8(lo, hi), A, oacc);
;             }
.LBB0_519:
	s_setprio 0
	s_waitcnt lgkmcnt(0)
	s_barrier
	s_and_b64 vcc, exec, s[56:57]
	v_mov_b32_e32 v1, v79
	v_mov_b32_e32 v2, v55
	s_mov_b32 s56, s63
	s_cbranch_vccnz .LBB0_506
.LBB0_520:
	s_setprio 1
	v_add_u32_e32 v3, 0x11c00, v2
	ds_read_b128 v[4:7], v1
	ds_read_b64_tr_b16 v[8:9], v3
	ds_read_b64_tr_b16 v[10:11], v3 offset:768
	ds_read_b128 v[204:207], v1 offset:32
	ds_read_b64_tr_b16 v[208:209], v3 offset:3072
	ds_read_b64_tr_b16 v[210:211], v3 offset:3840
	s_cmp_eq_u32 s56, 2
	s_cbranch_scc1 .Lhg_two
	ds_read_b128 v[212:215], v1 offset:64
	ds_read_b64_tr_b16 v[216:217], v3 offset:6144
	ds_read_b64_tr_b16 v[218:219], v3 offset:6912
	ds_read_b128 v[220:223], v1 offset:96
	ds_read_b64_tr_b16 v[224:225], v3 offset:9216
	ds_read_b64_tr_b16 v[226:227], v3 offset:9984
	s_waitcnt lgkmcnt(9)
	v_mfma_f32_32x32x16_bf16 v[32:47], v[8:11], v[4:7], v[32:47]
	s_waitcnt lgkmcnt(6)
	v_mfma_f32_32x32x16_bf16 v[32:47], v[208:211], v[204:207], v[32:47]
	s_waitcnt lgkmcnt(3)
	v_mfma_f32_32x32x16_bf16 v[32:47], v[216:219], v[212:215], v[32:47]
	s_waitcnt lgkmcnt(0)
	v_mfma_f32_32x32x16_bf16 v[32:47], v[224:227], v[220:223], v[32:47]
	s_branch .Lhg_avdone
